# static priority raise on waves 0-3 instead of 4-7 (setprio flips removed)
# baseline (speedup 1.0000x reference)
_Z11mega_kernel6Params:
	v_readfirstlane_b32 s94, v0
	s_nop 3
	s_and_b32 s94, s94, 0x3ff
	s_lshr_b32 s94, s94, 6
	s_cmp_lt_u32 s94, 4
	s_cbranch_scc0 .Lprio_done
	s_setprio 1
